# rowpass x4: prefetch next row loads into 2nd reg set (counted vmcnt)
# baseline (speedup 1.0000x reference)
.LBB0_520:
	s_cmp_lt_i32 s88, 4
	s_cselect_b64 s[0:1], -1, 0
	s_and_b64 s[6:7], s[0:1], s[2:3]
	s_andn2_b64 vcc, exec, s[6:7]
	s_cbranch_vccnz .LBB0_526
	s_lshl_b32 s2, s66, 3
	s_lshl_b32 s0, s66, 7
	s_and_b32 s0, s0, 0xfffff000
	s_and_b32 s1, s2, 0xf8
	s_add_i32 s3, s0, 0x1000
	s_or_b32 s4, s0, s1
	s_cmpk_eq_i32 s68, 0x100
	s_cselect_b64 s[8:9], -1, 0
	s_and_b64 s[0:1], s[8:9], exec
	s_cselect_b32 s2, s4, s2
	s_cselect_b32 s12, s3, 0x8000
	s_add_i32 s13, s2, s96
	s_cmp_ge_i32 s13, s12
	s_cbranch_scc1 .LBB0_526
	v_lshlrev_b32_e32 v14, 4, v177
	global_load_dwordx4 v[2:5], v14, s[60:61]
	global_load_dwordx4 v[6:9], v14, s[60:61] offset:1024
	global_load_dwordx4 v[10:13], v14, s[60:61] offset:2048
	s_nop 0
	global_load_dwordx4 v[14:17], v14, s[60:61] offset:3072
	v_mbcnt_lo_u32_b32 v18, -1, 0
	v_mbcnt_hi_u32_b32 v18, -1, v18
	v_and_b32_e32 v19, 64, v18
	v_add_u32_e32 v19, 64, v19
	v_xor_b32_e32 v20, 1, v18
	v_cmp_lt_i32_e32 vcc, v20, v19
	v_readlane_b32 s4, v252, 2
	s_lshl_b32 s3, s68, 3
	v_cndmask_b32_e32 v20, v18, v20, vcc
	v_lshlrev_b32_e32 v26, 2, v20
	v_xor_b32_e32 v20, 2, v18
	v_cmp_lt_i32_e32 vcc, v20, v19
	v_readlane_b32 s5, v252, 3
	s_and_b64 s[0:1], s[8:9], exec
	v_cndmask_b32_e32 v20, v18, v20, vcc
	v_lshlrev_b32_e32 v27, 2, v20
	v_xor_b32_e32 v20, 4, v18
	v_cmp_lt_i32_e32 vcc, v20, v19
	s_cselect_b32 s14, 0x100, s3
	s_lshl_b32 s3, s66, 8
	v_cndmask_b32_e32 v20, v18, v20, vcc
	v_lshlrev_b32_e32 v28, 2, v20
	v_xor_b32_e32 v20, 8, v18
	v_cmp_lt_i32_e32 vcc, v20, v19
	s_and_b32 s3, s3, 0xffffe000
	s_add_i32 s3, s96, s3
	v_cndmask_b32_e32 v20, v18, v20, vcc
	v_lshlrev_b32_e32 v29, 2, v20
	v_xor_b32_e32 v20, 16, v18
	v_cmp_lt_i32_e32 vcc, v20, v19
	v_cmp_eq_u32_e64 s[0:1], 0, v177
	s_mov_b32 s16, 0xffff0000
	v_cndmask_b32_e32 v20, v18, v20, vcc
	v_lshlrev_b32_e32 v30, 2, v20
	v_xor_b32_e32 v20, 32, v18
	v_cmp_lt_i32_e32 vcc, v20, v19
	v_mov_b32_e32 v19, 0
	v_mov_b32_e32 v32, 0x358637bd
	v_cndmask_b32_e32 v18, v18, v20, vcc
	v_lshlrev_b32_e32 v31, 2, v18
	v_lshlrev_b32_e32 v18, 3, v177
	v_lshl_add_u64 v[20:21], s[4:5], 0, v[18:19]
	v_readlane_b32 s4, v253, 52
	v_readlane_b32 s5, v253, 53
	s_mov_b32 s17, 0xf800000
	v_mov_b32_e32 v33, 0x260
	v_lshl_add_u64 v[22:23], s[4:5], 0, v[18:19]
	s_and_b32 s4, s66, 31
	s_lshl_b32 s4, s4, 4
	s_add_i32 s3, s3, s4
	s_sub_i32 s2, s3, s2
	s_add_i32 s15, s2, 0xf00
	s_movk_i32 s18, 0x7fff
	s_and_b64 s[2:3], s[8:9], exec
	s_cselect_b32 s2, s15, s13
	s_ashr_i32 s3, s2, 31
	s_lshl_b64 s[4:5], s[2:3], 11
	v_lshl_add_u64 v[98:99], v[20:21], 0, s[4:5]
	v_lshl_add_u64 v[100:101], v[22:23], 0, s[4:5]
	s_lshl_b64 s[2:3], s[2:3], 2
	s_add_u32 s2, s75, s2
	s_addc_u32 s3, s69, s3
	global_load_dwordx2 v[80:81], v[98:99], off
	global_load_dwordx2 v[82:83], v[98:99], off offset:512
	global_load_dwordx2 v[84:85], v[98:99], off offset:1024
	global_load_dwordx2 v[86:87], v[98:99], off offset:1536
	global_load_dwordx2 v[88:89], v[100:101], off
	global_load_dwordx2 v[90:91], v[100:101], off offset:512
	global_load_dwordx2 v[92:93], v[100:101], off offset:1024
	global_load_dwordx2 v[94:95], v[100:101], off offset:1536
	global_load_dword v96, v19, s[2:3]
	s_waitcnt vmcnt(0)
	s_branch .Lrp1_body

.LBB0_524:
	s_waitcnt vmcnt(5)
.Lrp1_body:
	v_mov_b32_e32 v34, v80
	v_mov_b32_e32 v35, v81
	v_mov_b32_e32 v36, v82
	v_mov_b32_e32 v37, v83
	v_mov_b32_e32 v38, v84
	v_mov_b32_e32 v39, v85
	v_mov_b32_e32 v40, v86
	v_mov_b32_e32 v41, v87
	v_mov_b32_e32 v42, v88
	v_mov_b32_e32 v43, v89
	v_mov_b32_e32 v44, v90
	v_mov_b32_e32 v45, v91
	v_mov_b32_e32 v46, v92
	v_mov_b32_e32 v47, v93
	v_mov_b32_e32 v48, v94
	v_mov_b32_e32 v49, v95
	v_mov_b32_e32 v18, v96
	s_and_b64 s[2:3], s[8:9], exec
	s_cselect_b32 s2, s15, s13
	s_ashr_i32 s3, s2, 31
	s_lshl_b64 s[4:5], s[2:3], 11
	s_lshl_b64 s[2:3], s[2:3], 2
	s_add_u32 s10, s75, s2
	v_lshl_add_u64 v[24:25], v[22:23], 0, s[4:5]
	s_addc_u32 s11, s69, s3
	s_add_i32 s2, s13, s14
	s_cmp_lt_i32 s2, s12
	s_cbranch_scc0 .Lrp1_skip
	s_sub_i32 s3, s15, s14
	s_and_b64 s[4:5], s[8:9], exec
	s_cselect_b32 s2, s3, s2
	s_ashr_i32 s3, s2, 31
	s_lshl_b64 s[4:5], s[2:3], 11
	v_lshl_add_u64 v[98:99], v[20:21], 0, s[4:5]
	v_lshl_add_u64 v[100:101], v[22:23], 0, s[4:5]
	s_lshl_b64 s[2:3], s[2:3], 2
	s_add_u32 s2, s75, s2
	s_addc_u32 s3, s69, s3
	global_load_dwordx2 v[80:81], v[98:99], off
	global_load_dwordx2 v[82:83], v[98:99], off offset:512
	global_load_dwordx2 v[84:85], v[98:99], off offset:1024
	global_load_dwordx2 v[86:87], v[98:99], off offset:1536
	global_load_dwordx2 v[88:89], v[100:101], off
	global_load_dwordx2 v[90:91], v[100:101], off offset:512
	global_load_dwordx2 v[92:93], v[100:101], off offset:1024
	global_load_dwordx2 v[94:95], v[100:101], off offset:1536
	global_load_dword v96, v19, s[2:3]
.Lrp1_skip:
	v_lshlrev_b32_e32 v50, 16, v34
	v_and_b32_e32 v51, 0xffff0000, v34
	v_alignbit_b32 v34, v35, v34, 16
	v_and_b32_e32 v35, 0xffff0000, v35
	v_lshlrev_b32_e32 v52, 16, v36
	v_and_b32_e32 v53, 0xffff0000, v36
	v_alignbit_b32 v36, v37, v36, 16
	v_and_b32_e32 v37, 0xffff0000, v37
	v_lshlrev_b32_e32 v54, 16, v38
	v_and_b32_e32 v55, 0xffff0000, v38
	v_alignbit_b32 v38, v39, v38, 16
	v_and_b32_e32 v39, 0xffff0000, v39
	v_and_b32_e32 v34, 0xffff0000, v34
	v_and_b32_e32 v36, 0xffff0000, v36
	v_mul_f32_e32 v58, v51, v51
	v_mul_f32_e32 v59, v35, v35
	v_mul_f32_e32 v60, v53, v53
	v_mul_f32_e32 v61, v37, v37
	v_lshlrev_b32_e32 v56, 16, v40
	v_and_b32_e32 v57, 0xffff0000, v40
	v_alignbit_b32 v40, v41, v40, 16
	v_and_b32_e32 v41, 0xffff0000, v41
	v_and_b32_e32 v38, 0xffff0000, v38
	v_mul_f32_e32 v62, v55, v55
	v_mul_f32_e32 v63, v39, v39
	v_fmac_f32_e32 v58, v50, v50
	v_fmac_f32_e32 v59, v34, v34
	v_fmac_f32_e32 v60, v52, v52
	v_fmac_f32_e32 v61, v36, v36
	v_and_b32_e32 v40, 0xffff0000, v40
	v_mul_f32_e32 v64, v57, v57
	v_mul_f32_e32 v65, v41, v41
	v_fmac_f32_e32 v62, v54, v54
	v_fmac_f32_e32 v63, v38, v38
	v_add_f32_e32 v58, v58, v59
	v_add_f32_e32 v59, v60, v61
	v_fmac_f32_e32 v64, v56, v56
	v_fmac_f32_e32 v65, v40, v40
	v_add_f32_e32 v60, v62, v63
	v_add_f32_e32 v58, v58, v59
	v_add_f32_e32 v61, v64, v65
	v_add_f32_e32 v58, v58, v60
	v_add_f32_e32 v60, v58, v61
	ds_bpermute_b32 v61, v26, v60
	v_lshlrev_b32_e32 v58, 16, v42
	v_and_b32_e32 v59, 0xffff0000, v42
	v_alignbit_b32 v42, v43, v42, 16
	v_pk_mul_f32 v[50:51], v[2:3], v[50:51]
	s_waitcnt lgkmcnt(0)
	v_add_f32_e32 v62, v60, v61
	ds_bpermute_b32 v63, v27, v62
	v_lshlrev_b32_e32 v60, 16, v44
	v_and_b32_e32 v61, 0xffff0000, v44
	v_alignbit_b32 v44, v45, v44, 16
	v_pk_mul_f32 v[52:53], v[6:7], v[52:53]
	s_waitcnt lgkmcnt(0)
	v_add_f32_e32 v64, v62, v63
	ds_bpermute_b32 v65, v28, v64
	v_pk_mul_f32 v[34:35], v[4:5], v[34:35]
	v_pk_mul_f32 v[36:37], v[8:9], v[36:37]
	v_and_b32_e32 v43, 0xffff0000, v43
	v_and_b32_e32 v45, 0xffff0000, v45
	s_waitcnt lgkmcnt(0)
	v_add_f32_e32 v66, v64, v65
	ds_bpermute_b32 v67, v29, v66
	v_and_b32_e32 v42, 0xffff0000, v42
	v_and_b32_e32 v44, 0xffff0000, v44
	v_lshlrev_b32_e32 v62, 16, v46
	v_and_b32_e32 v63, 0xffff0000, v46
	s_waitcnt lgkmcnt(0)
	v_add_f32_e32 v66, v66, v67
	ds_bpermute_b32 v67, v30, v66
	v_alignbit_b32 v46, v47, v46, 16
	v_pk_mul_f32 v[54:55], v[10:11], v[54:55]
	v_pk_mul_f32 v[38:39], v[12:13], v[38:39]
	v_and_b32_e32 v47, 0xffff0000, v47
	s_waitcnt lgkmcnt(0)
	v_add_f32_e32 v66, v66, v67
	ds_bpermute_b32 v67, v31, v66
	v_lshlrev_b32_e32 v64, 16, v48
	v_and_b32_e32 v65, 0xffff0000, v48
	v_alignbit_b32 v48, v49, v48, 16
	v_and_b32_e32 v46, 0xffff0000, v46
	s_waitcnt lgkmcnt(0)
	v_add_f32_e32 v66, v66, v67
	v_fmamk_f32 v66, v66, 0x3a800000, v32
	v_mul_f32_e32 v67, 0x4f800000, v66
	v_cmp_gt_f32_e32 vcc, s17, v66
	v_pk_mul_f32 v[56:57], v[14:15], v[56:57]
	v_pk_mul_f32 v[40:41], v[16:17], v[40:41]
	v_cndmask_b32_e32 v66, v66, v67, vcc
	v_sqrt_f32_e32 v67, v66
	v_and_b32_e32 v49, 0xffff0000, v49
	v_and_b32_e32 v48, 0xffff0000, v48
	v_add_u32_e32 v68, -1, v67
	v_add_u32_e32 v69, 1, v67
	v_fma_f32 v70, -v68, v67, v66
	v_fma_f32 v71, -v69, v67, v66
	v_cmp_ge_f32_e64 s[4:5], 0, v70
	s_nop 1
	v_cndmask_b32_e64 v67, v67, v68, s[4:5]
	v_cmp_lt_f32_e64 s[4:5], 0, v71
	s_nop 1
	v_cndmask_b32_e64 v67, v67, v69, s[4:5]
	v_mul_f32_e32 v68, 0x37800000, v67
	v_cndmask_b32_e32 v67, v67, v68, vcc
	v_cmp_class_f32_e32 vcc, v66, v33
	s_nop 1
	v_cndmask_b32_e32 v66, v67, v66, vcc
	v_div_scale_f32 v67, s[2:3], v66, v66, 0.5
	v_rcp_f32_e32 v68, v67
	v_div_scale_f32 v69, vcc, 0.5, v66, 0.5
	v_fma_f32 v70, -v67, v68, 1.0
	v_fmac_f32_e32 v68, v70, v68
	v_mul_f32_e32 v70, v69, v68
	v_fma_f32 v71, -v67, v70, v69
	v_fmac_f32_e32 v70, v71, v68
	v_fma_f32 v67, -v67, v70, v69
	v_div_fmas_f32 v67, v67, v68, v70
	v_div_fixup_f32 v66, v67, v66, 0.5
	v_pk_mul_f32 v[50:51], v[50:51], v[66:67] op_sel_hi:[1,0]
	v_pk_mul_f32 v[34:35], v[34:35], v[66:67] op_sel_hi:[1,0]
	v_pk_mul_f32 v[52:53], v[52:53], v[66:67] op_sel_hi:[1,0]
	v_pk_mul_f32 v[36:37], v[36:37], v[66:67] op_sel_hi:[1,0]
	v_pk_fma_f32 v[34:35], v[18:19], v[42:43], v[34:35] op_sel_hi:[0,1,1]
	v_pk_fma_f32 v[42:43], v[18:19], v[58:59], v[50:51] op_sel_hi:[0,1,1]
	v_pk_fma_f32 v[36:37], v[18:19], v[44:45], v[36:37] op_sel_hi:[0,1,1]
	v_pk_fma_f32 v[44:45], v[18:19], v[60:61], v[52:53] op_sel_hi:[0,1,1]
	v_pk_mul_f32 v[54:55], v[54:55], v[66:67] op_sel_hi:[1,0]
	v_pk_mul_f32 v[38:39], v[38:39], v[66:67] op_sel_hi:[1,0]
	v_mul_f32_e32 v50, v43, v43
	v_mul_f32_e32 v51, v35, v35
	v_mul_f32_e32 v52, v45, v45
	v_mul_f32_e32 v53, v37, v37
	v_pk_mul_f32 v[56:57], v[56:57], v[66:67] op_sel_hi:[1,0]
	v_pk_fma_f32 v[38:39], v[18:19], v[46:47], v[38:39] op_sel_hi:[0,1,1]
	v_pk_fma_f32 v[46:47], v[18:19], v[62:63], v[54:55] op_sel_hi:[0,1,1]
	v_fmac_f32_e32 v50, v42, v42
	v_fmac_f32_e32 v51, v34, v34
	v_fmac_f32_e32 v52, v44, v44
	v_fmac_f32_e32 v53, v36, v36
	v_pk_mul_f32 v[40:41], v[40:41], v[66:67] op_sel_hi:[1,0]
	v_mul_f32_e32 v54, v47, v47
	v_mul_f32_e32 v55, v39, v39
	v_add_f32_e32 v50, v50, v51
	v_add_f32_e32 v51, v52, v53
	v_pk_fma_f32 v[40:41], v[18:19], v[48:49], v[40:41] op_sel_hi:[0,1,1]
	v_pk_fma_f32 v[48:49], v[18:19], v[64:65], v[56:57] op_sel_hi:[0,1,1]
	v_fmac_f32_e32 v54, v46, v46
	v_fmac_f32_e32 v55, v38, v38
	v_add_f32_e32 v50, v50, v51
	v_mul_f32_e32 v18, v49, v49
	v_mul_f32_e32 v51, v41, v41
	v_add_f32_e32 v52, v54, v55
	v_fmac_f32_e32 v18, v48, v48
	v_fmac_f32_e32 v51, v40, v40
	v_add_f32_e32 v50, v52, v50
	v_add_f32_e32 v18, v18, v51
	v_add_f32_e32 v18, v18, v50
	ds_bpermute_b32 v50, v26, v18
	s_waitcnt lgkmcnt(0)
	v_add_f32_e32 v18, v18, v50
	ds_bpermute_b32 v50, v27, v18
	s_waitcnt lgkmcnt(0)
	v_add_f32_e32 v18, v18, v50
	ds_bpermute_b32 v50, v28, v18
	s_waitcnt lgkmcnt(0)
	v_add_f32_e32 v18, v18, v50
	ds_bpermute_b32 v50, v29, v18
	s_waitcnt lgkmcnt(0)
	v_add_f32_e32 v18, v18, v50
	ds_bpermute_b32 v50, v30, v18
	s_waitcnt lgkmcnt(0)
	v_add_f32_e32 v18, v18, v50
	ds_bpermute_b32 v50, v31, v18
	s_waitcnt lgkmcnt(0)
	v_add_f32_e32 v18, v18, v50
	v_fmamk_f32 v18, v18, 0x3a800000, v32
	v_mul_f32_e32 v50, 0x4f800000, v18
	v_cmp_gt_f32_e32 vcc, s17, v18
	s_nop 1
	v_cndmask_b32_e32 v18, v18, v50, vcc
	v_sqrt_f32_e32 v50, v18
	s_nop 0
	v_add_u32_e32 v51, -1, v50
	v_add_u32_e32 v52, 1, v50
	v_fma_f32 v53, -v51, v50, v18
	v_fma_f32 v54, -v52, v50, v18
	v_cmp_ge_f32_e64 s[4:5], 0, v53
	s_nop 1
	v_cndmask_b32_e64 v50, v50, v51, s[4:5]
	v_cmp_lt_f32_e64 s[4:5], 0, v54
	s_nop 1
	v_cndmask_b32_e64 v50, v50, v52, s[4:5]
	v_mul_f32_e32 v51, 0x37800000, v50
	v_cndmask_b32_e32 v50, v50, v51, vcc
	v_cmp_class_f32_e32 vcc, v18, v33
	s_nop 1
	v_cndmask_b32_e32 v18, v50, v18, vcc
	v_div_scale_f32 v50, s[2:3], v18, v18, 1.0
	v_rcp_f32_e32 v51, v50
	v_div_scale_f32 v52, vcc, 1.0, v18, 1.0
	v_fma_f32 v53, -v50, v51, 1.0
	v_fmac_f32_e32 v51, v53, v51
	v_mul_f32_e32 v53, v52, v51
	v_fma_f32 v54, -v50, v53, v52
	v_fmac_f32_e32 v53, v54, v51
	v_fma_f32 v50, -v50, v53, v52
	v_div_fmas_f32 v50, v50, v51, v53
	v_div_fixup_f32 v50, v50, v18, 1.0
	v_mul_f32_e32 v42, v42, v50
	v_mul_f32_e32 v34, v34, v50
	v_mul_f32_e32 v43, v43, v50
	v_mul_f32_e32 v35, v35, v50
	v_bfe_u32 v51, v42, 16, 1
	v_bfe_u32 v53, v34, 16, 1
	v_bfe_u32 v52, v43, 16, 1
	v_bfe_u32 v54, v35, 16, 1
	v_add3_u32 v42, v42, v51, s18
	v_add3_u32 v34, v34, v53, s18
	v_add3_u32 v43, v43, v52, s18
	v_add3_u32 v35, v35, v54, s18
	v_lshrrev_b32_e32 v42, 16, v42
	v_lshrrev_b32_e32 v51, 16, v34
	v_mul_f32_e32 v44, v44, v50
	v_and_or_b32 v34, v43, s16, v42
	v_and_or_b32 v35, v35, s16, v51
	global_store_dwordx2 v[24:25], v[34:35], off
	v_mul_f32_e32 v34, v45, v50
	v_bfe_u32 v35, v44, 16, 1
	v_add3_u32 v35, v44, v35, s18
	v_bfe_u32 v42, v34, 16, 1
	v_lshrrev_b32_e32 v35, 16, v35
	v_add3_u32 v34, v34, v42, s18
	v_and_or_b32 v34, v34, s16, v35
	v_mul_f32_e32 v35, v36, v50
	v_mul_f32_e32 v36, v37, v50
	v_bfe_u32 v37, v35, 16, 1
	v_add3_u32 v35, v35, v37, s18
	v_bfe_u32 v37, v36, 16, 1
	v_lshrrev_b32_e32 v35, 16, v35
	v_add3_u32 v36, v36, v37, s18
	v_and_or_b32 v35, v36, s16, v35
	global_store_dwordx2 v[24:25], v[34:35], off offset:512
	v_mul_f32_e32 v34, v46, v50
	v_mul_f32_e32 v35, v47, v50
	v_bfe_u32 v36, v34, 16, 1
	v_add3_u32 v34, v34, v36, s18
	v_bfe_u32 v36, v35, 16, 1
	v_lshrrev_b32_e32 v34, 16, v34
	v_add3_u32 v35, v35, v36, s18
	v_and_or_b32 v34, v35, s16, v34
	v_mul_f32_e32 v35, v38, v50
	v_mul_f32_e32 v36, v39, v50
	v_bfe_u32 v37, v35, 16, 1
	v_add3_u32 v35, v35, v37, s18
	v_bfe_u32 v37, v36, 16, 1
	v_lshrrev_b32_e32 v35, 16, v35
	v_add3_u32 v36, v36, v37, s18
	v_and_or_b32 v35, v36, s16, v35
	global_store_dwordx2 v[24:25], v[34:35], off offset:1024
	v_mul_f32_e32 v34, v48, v50
	v_mul_f32_e32 v35, v49, v50
	v_bfe_u32 v36, v34, 16, 1
	v_add3_u32 v34, v34, v36, s18
	v_bfe_u32 v36, v35, 16, 1
	v_lshrrev_b32_e32 v34, 16, v34
	v_add3_u32 v35, v35, v36, s18
	v_and_or_b32 v34, v35, s16, v34
	v_mul_f32_e32 v35, v40, v50
	v_mul_f32_e32 v36, v41, v50
	v_bfe_u32 v37, v35, 16, 1
	v_add3_u32 v35, v35, v37, s18
	v_bfe_u32 v37, v36, 16, 1
	v_lshrrev_b32_e32 v35, 16, v35
	v_add3_u32 v36, v36, v37, s18
	v_and_or_b32 v35, v36, s16, v35
	global_store_dwordx2 v[24:25], v[34:35], off offset:1536
	s_and_saveexec_b64 s[2:3], s[0:1]
	s_cbranch_execz .LBB0_523
	global_store_dword v19, v18, s[10:11]
	s_branch .LBB0_523

.LBB0_1123:
	s_cmp_lt_i32 s88, 10
	s_cselect_b64 s[0:1], -1, 0
	s_and_b64 s[6:7], s[0:1], s[2:3]
	s_andn2_b64 vcc, exec, s[6:7]
	s_cbranch_vccnz .LBB0_1140
	s_lshl_b32 s2, s66, 3
	s_lshl_b32 s0, s66, 7
	s_and_b32 s0, s0, 0xfffff000
	s_and_b32 s1, s2, 0xf8
	s_add_i32 s3, s0, 0x1000
	s_or_b32 s4, s0, s1
	s_cmpk_eq_i32 s68, 0x100
	s_cselect_b64 s[8:9], -1, 0
	s_and_b64 s[0:1], s[8:9], exec
	s_cselect_b32 s2, s4, s2
	s_cselect_b32 s12, s3, 0x8000
	s_add_i32 s13, s2, s96
	s_cmp_ge_i32 s13, s12
	s_cbranch_scc1 .LBB0_1129
	v_readlane_b32 s36, v253, 20
	v_lshlrev_b32_e32 v1, 4, v177
	v_readlane_b32 s50, v253, 34
	v_readlane_b32 s51, v253, 35
	s_nop 4
	global_load_dwordx4 v[2:5], v1, s[50:51]
	global_load_dwordx4 v[6:9], v1, s[50:51] offset:1024
	global_load_dwordx4 v[10:13], v1, s[50:51] offset:2048
	global_load_dwordx4 v[14:17], v1, s[50:51] offset:3072
	v_mbcnt_lo_u32_b32 v1, -1, 0
	v_mbcnt_hi_u32_b32 v18, -1, v1
	v_and_b32_e32 v1, 64, v18
	v_add_u32_e32 v19, 64, v1
	v_xor_b32_e32 v1, 1, v18
	v_cmp_lt_i32_e32 vcc, v1, v19
	v_xor_b32_e32 v20, 2, v18
	v_readlane_b32 s4, v252, 2
	v_cndmask_b32_e32 v1, v18, v1, vcc
	v_cmp_lt_i32_e32 vcc, v20, v19
	s_lshl_b32 s3, s68, 3
	v_readlane_b32 s5, v252, 3
	v_cndmask_b32_e32 v20, v18, v20, vcc
	v_lshlrev_b32_e32 v26, 2, v20
	v_xor_b32_e32 v20, 4, v18
	v_cmp_lt_i32_e32 vcc, v20, v19
	s_mov_b64 s[14:15], s[50:51]
	s_and_b64 s[0:1], s[8:9], exec
	v_cndmask_b32_e32 v20, v18, v20, vcc
	v_lshlrev_b32_e32 v27, 2, v20
	v_xor_b32_e32 v20, 8, v18
	v_cmp_lt_i32_e32 vcc, v20, v19
	s_cselect_b32 s14, 0x100, s3
	s_lshl_b32 s3, s66, 8
	v_cndmask_b32_e32 v20, v18, v20, vcc
	v_lshlrev_b32_e32 v28, 2, v20
	v_xor_b32_e32 v20, 16, v18
	v_cmp_lt_i32_e32 vcc, v20, v19
	s_and_b32 s3, s3, 0xffffe000
	s_add_i32 s3, s96, s3
	v_cndmask_b32_e32 v20, v18, v20, vcc
	v_lshlrev_b32_e32 v29, 2, v20
	v_xor_b32_e32 v20, 32, v18
	v_cmp_lt_i32_e32 vcc, v20, v19
	v_mov_b32_e32 v19, 0
	v_lshlrev_b32_e32 v1, 2, v1
	v_cndmask_b32_e32 v18, v18, v20, vcc
	v_lshlrev_b32_e32 v30, 2, v18
	v_lshlrev_b32_e32 v18, 3, v177
	v_lshl_add_u64 v[20:21], s[4:5], 0, v[18:19]
	v_readlane_b32 s4, v253, 52
	v_readlane_b32 s5, v253, 53
	v_cmp_eq_u32_e64 s[0:1], 0, v177
	s_mov_b32 s16, 0xffff0000
	s_waitcnt vmcnt(0)
	v_lshl_add_u64 v[22:23], s[4:5], 0, v[18:19]
	s_and_b32 s4, s66, 31
	s_lshl_b32 s4, s4, 4
	s_add_i32 s3, s3, s4
	s_sub_i32 s2, s3, s2
	s_add_i32 s15, s2, 0xf00
	v_mov_b32_e32 v31, 0x358637bd
	s_mov_b32 s17, 0xf800000
	v_mov_b32_e32 v32, 0x260
	s_movk_i32 s18, 0x7fff
	v_readlane_b32 s37, v253, 21
	v_readlane_b32 s38, v253, 22
	v_readlane_b32 s39, v253, 23
	v_readlane_b32 s40, v253, 24
	v_readlane_b32 s41, v253, 25
	v_readlane_b32 s42, v253, 26
	v_readlane_b32 s43, v253, 27
	v_readlane_b32 s44, v253, 28
	v_readlane_b32 s45, v253, 29
	v_readlane_b32 s46, v253, 30
	v_readlane_b32 s47, v253, 31
	v_readlane_b32 s48, v253, 32
	v_readlane_b32 s49, v253, 33
	s_and_b64 s[2:3], s[8:9], exec
	s_cselect_b32 s2, s15, s13
	s_ashr_i32 s3, s2, 31
	s_lshl_b64 s[4:5], s[2:3], 11
	v_lshl_add_u64 v[98:99], v[20:21], 0, s[4:5]
	v_lshl_add_u64 v[100:101], v[22:23], 0, s[4:5]
	s_lshl_b64 s[2:3], s[2:3], 2
	s_add_u32 s2, s75, s2
	s_addc_u32 s3, s69, s3
	global_load_dwordx2 v[80:81], v[98:99], off
	global_load_dwordx2 v[82:83], v[98:99], off offset:512
	global_load_dwordx2 v[84:85], v[98:99], off offset:1024
	global_load_dwordx2 v[86:87], v[98:99], off offset:1536
	global_load_dwordx2 v[88:89], v[100:101], off
	global_load_dwordx2 v[90:91], v[100:101], off offset:512
	global_load_dwordx2 v[92:93], v[100:101], off offset:1024
	global_load_dwordx2 v[94:95], v[100:101], off offset:1536
	global_load_dword v96, v19, s[2:3]
	s_waitcnt vmcnt(0)
	s_branch .Lrp2_body

.Lrp2_skip:
	v_and_b32_e32 v51, 0xffff0000, v34
	v_alignbit_b32 v33, v35, v34, 16
	v_and_b32_e32 v35, 0xffff0000, v35
	v_lshlrev_b32_e32 v52, 16, v36
	v_and_b32_e32 v53, 0xffff0000, v36
	v_alignbit_b32 v36, v37, v36, 16
	v_and_b32_e32 v37, 0xffff0000, v37
	v_lshlrev_b32_e32 v50, 16, v34
	v_lshlrev_b32_e32 v54, 16, v38
	v_and_b32_e32 v55, 0xffff0000, v38
	v_alignbit_b32 v38, v39, v38, 16
	v_and_b32_e32 v39, 0xffff0000, v39
	v_and_b32_e32 v34, 0xffff0000, v33
	v_and_b32_e32 v36, 0xffff0000, v36
	v_mul_f32_e32 v33, v51, v51
	v_mul_f32_e32 v58, v35, v35
	v_mul_f32_e32 v59, v53, v53
	v_mul_f32_e32 v60, v37, v37
	v_lshlrev_b32_e32 v56, 16, v40
	v_and_b32_e32 v57, 0xffff0000, v40
	v_alignbit_b32 v40, v41, v40, 16
	v_and_b32_e32 v41, 0xffff0000, v41
	v_and_b32_e32 v38, 0xffff0000, v38
	v_mul_f32_e32 v61, v55, v55
	v_mul_f32_e32 v62, v39, v39
	v_fmac_f32_e32 v33, v50, v50
	v_fmac_f32_e32 v58, v34, v34
	v_fmac_f32_e32 v59, v52, v52
	v_fmac_f32_e32 v60, v36, v36
	v_and_b32_e32 v40, 0xffff0000, v40
	v_mul_f32_e32 v63, v57, v57
	v_mul_f32_e32 v64, v41, v41
	v_fmac_f32_e32 v61, v54, v54
	v_fmac_f32_e32 v62, v38, v38
	v_add_f32_e32 v33, v33, v58
	v_add_f32_e32 v58, v59, v60
	v_fmac_f32_e32 v63, v56, v56
	v_fmac_f32_e32 v64, v40, v40
	v_add_f32_e32 v59, v61, v62
	v_add_f32_e32 v33, v33, v58
	v_add_f32_e32 v60, v63, v64
	v_add_f32_e32 v33, v33, v59
	v_add_f32_e32 v33, v33, v60
	ds_bpermute_b32 v60, v1, v33
	v_lshlrev_b32_e32 v58, 16, v42
	v_and_b32_e32 v59, 0xffff0000, v42
	v_alignbit_b32 v42, v43, v42, 16
	v_and_b32_e32 v61, 0xffff0000, v44
	s_waitcnt lgkmcnt(0)
	v_add_f32_e32 v33, v33, v60
	ds_bpermute_b32 v62, v26, v33
	v_lshlrev_b32_e32 v60, 16, v44
	v_alignbit_b32 v44, v45, v44, 16
	v_pk_mul_f32 v[50:51], v[2:3], v[50:51]
	v_pk_mul_f32 v[52:53], v[6:7], v[52:53]
	s_waitcnt lgkmcnt(0)
	v_add_f32_e32 v33, v33, v62
	ds_bpermute_b32 v64, v27, v33
	v_pk_mul_f32 v[34:35], v[4:5], v[34:35]
	v_pk_mul_f32 v[36:37], v[8:9], v[36:37]
	v_and_b32_e32 v43, 0xffff0000, v43
	v_and_b32_e32 v45, 0xffff0000, v45
	s_waitcnt lgkmcnt(0)
	v_add_f32_e32 v33, v33, v64
	ds_bpermute_b32 v66, v28, v33
	v_and_b32_e32 v42, 0xffff0000, v42
	v_and_b32_e32 v44, 0xffff0000, v44
	v_lshlrev_b32_e32 v62, 16, v46
	v_and_b32_e32 v63, 0xffff0000, v46
	s_waitcnt lgkmcnt(0)
	v_add_f32_e32 v33, v33, v66
	ds_bpermute_b32 v66, v29, v33
	v_alignbit_b32 v46, v47, v46, 16
	v_pk_mul_f32 v[54:55], v[10:11], v[54:55]
	v_pk_mul_f32 v[38:39], v[12:13], v[38:39]
	v_and_b32_e32 v47, 0xffff0000, v47
	s_waitcnt lgkmcnt(0)
	v_add_f32_e32 v33, v33, v66
	ds_bpermute_b32 v66, v30, v33
	v_lshlrev_b32_e32 v64, 16, v48
	v_and_b32_e32 v65, 0xffff0000, v48
	v_alignbit_b32 v48, v49, v48, 16
	v_and_b32_e32 v46, 0xffff0000, v46
	s_waitcnt lgkmcnt(0)
	v_add_f32_e32 v33, v33, v66
	v_fmamk_f32 v33, v33, 0x3a800000, v31
	v_mul_f32_e32 v66, 0x4f800000, v33
	v_cmp_gt_f32_e32 vcc, s17, v33
	v_pk_mul_f32 v[56:57], v[14:15], v[56:57]
	v_pk_mul_f32 v[40:41], v[16:17], v[40:41]
	v_cndmask_b32_e32 v33, v33, v66, vcc
	v_sqrt_f32_e32 v66, v33
	v_and_b32_e32 v49, 0xffff0000, v49
	v_and_b32_e32 v48, 0xffff0000, v48
	v_add_u32_e32 v67, -1, v66
	v_add_u32_e32 v68, 1, v66
	v_fma_f32 v69, -v67, v66, v33
	v_fma_f32 v70, -v68, v66, v33
	v_cmp_ge_f32_e64 s[4:5], 0, v69
	s_nop 1
	v_cndmask_b32_e64 v66, v66, v67, s[4:5]
	v_cmp_lt_f32_e64 s[4:5], 0, v70
	s_nop 1
	v_cndmask_b32_e64 v66, v66, v68, s[4:5]
	v_mul_f32_e32 v67, 0x37800000, v66
	v_cndmask_b32_e32 v66, v66, v67, vcc
	v_cmp_class_f32_e32 vcc, v33, v32
	s_nop 1
	v_cndmask_b32_e32 v33, v66, v33, vcc
	v_div_scale_f32 v66, s[2:3], v33, v33, 1.0
	v_rcp_f32_e32 v67, v66
	v_div_scale_f32 v68, vcc, 1.0, v33, 1.0
	v_fma_f32 v69, -v66, v67, 1.0
	v_fmac_f32_e32 v67, v69, v67
	v_mul_f32_e32 v69, v68, v67
	v_fma_f32 v70, -v66, v69, v68
	v_fmac_f32_e32 v69, v70, v67
	v_fma_f32 v66, -v66, v69, v68
	v_div_fmas_f32 v66, v66, v67, v69
	v_div_fixup_f32 v66, v66, v33, 1.0
	v_pk_mul_f32 v[50:51], v[50:51], v[66:67] op_sel_hi:[1,0]
	v_pk_mul_f32 v[34:35], v[34:35], v[66:67] op_sel_hi:[1,0]
	v_pk_mul_f32 v[52:53], v[52:53], v[66:67] op_sel_hi:[1,0]
	v_pk_mul_f32 v[36:37], v[36:37], v[66:67] op_sel_hi:[1,0]
	v_pk_fma_f32 v[34:35], v[18:19], v[42:43], v[34:35] op_sel_hi:[0,1,1]
	v_pk_fma_f32 v[42:43], v[18:19], v[58:59], v[50:51] op_sel_hi:[0,1,1]
	v_pk_fma_f32 v[36:37], v[18:19], v[44:45], v[36:37] op_sel_hi:[0,1,1]
	v_pk_fma_f32 v[44:45], v[18:19], v[60:61], v[52:53] op_sel_hi:[0,1,1]
	v_pk_mul_f32 v[54:55], v[54:55], v[66:67] op_sel_hi:[1,0]
	v_pk_mul_f32 v[38:39], v[38:39], v[66:67] op_sel_hi:[1,0]
	v_mul_f32_e32 v33, v43, v43
	v_mul_f32_e32 v50, v35, v35
	v_mul_f32_e32 v51, v45, v45
	v_mul_f32_e32 v52, v37, v37
	v_pk_mul_f32 v[56:57], v[56:57], v[66:67] op_sel_hi:[1,0]
	v_pk_fma_f32 v[38:39], v[18:19], v[46:47], v[38:39] op_sel_hi:[0,1,1]
	v_pk_fma_f32 v[46:47], v[18:19], v[62:63], v[54:55] op_sel_hi:[0,1,1]
	v_fmac_f32_e32 v33, v42, v42
	v_fmac_f32_e32 v50, v34, v34
	v_fmac_f32_e32 v51, v44, v44
	v_fmac_f32_e32 v52, v36, v36
	v_pk_mul_f32 v[40:41], v[40:41], v[66:67] op_sel_hi:[1,0]
	v_mul_f32_e32 v53, v47, v47
	v_mul_f32_e32 v54, v39, v39
	v_add_f32_e32 v33, v33, v50
	v_add_f32_e32 v50, v51, v52
	v_pk_fma_f32 v[40:41], v[18:19], v[48:49], v[40:41] op_sel_hi:[0,1,1]
	v_pk_fma_f32 v[48:49], v[18:19], v[64:65], v[56:57] op_sel_hi:[0,1,1]
	v_fmac_f32_e32 v53, v46, v46
	v_fmac_f32_e32 v54, v38, v38
	v_add_f32_e32 v33, v33, v50
	v_mul_f32_e32 v18, v49, v49
	v_mul_f32_e32 v50, v41, v41
	v_add_f32_e32 v51, v53, v54
	v_fmac_f32_e32 v18, v48, v48
	v_fmac_f32_e32 v50, v40, v40
	v_add_f32_e32 v33, v51, v33
	v_add_f32_e32 v18, v18, v50
	v_add_f32_e32 v18, v18, v33
	ds_bpermute_b32 v33, v1, v18
	s_waitcnt lgkmcnt(0)
	v_add_f32_e32 v18, v18, v33
	ds_bpermute_b32 v33, v26, v18
	s_waitcnt lgkmcnt(0)
	v_add_f32_e32 v18, v18, v33
	ds_bpermute_b32 v33, v27, v18
	s_waitcnt lgkmcnt(0)
	v_add_f32_e32 v18, v18, v33
	ds_bpermute_b32 v33, v28, v18
	s_waitcnt lgkmcnt(0)
	v_add_f32_e32 v18, v18, v33
	ds_bpermute_b32 v33, v29, v18
	s_waitcnt lgkmcnt(0)
	v_add_f32_e32 v18, v18, v33
	ds_bpermute_b32 v33, v30, v18
	s_waitcnt lgkmcnt(0)
	v_add_f32_e32 v18, v18, v33
	v_fmamk_f32 v18, v18, 0x3a800000, v31
	v_mul_f32_e32 v33, 0x4f800000, v18
	v_cmp_gt_f32_e32 vcc, s17, v18
	s_nop 1
	v_cndmask_b32_e32 v18, v18, v33, vcc
	v_sqrt_f32_e32 v33, v18
	s_nop 0
	v_add_u32_e32 v50, -1, v33
	v_add_u32_e32 v51, 1, v33
	v_fma_f32 v52, -v50, v33, v18
	v_fma_f32 v53, -v51, v33, v18
	v_cmp_ge_f32_e64 s[4:5], 0, v52
	s_nop 1
	v_cndmask_b32_e64 v33, v33, v50, s[4:5]
	v_cmp_lt_f32_e64 s[4:5], 0, v53
	s_nop 1
	v_cndmask_b32_e64 v33, v33, v51, s[4:5]
	v_mul_f32_e32 v50, 0x37800000, v33
	v_cndmask_b32_e32 v33, v33, v50, vcc
	v_cmp_class_f32_e32 vcc, v18, v32
	s_nop 1
	v_cndmask_b32_e32 v18, v33, v18, vcc
	v_div_scale_f32 v33, s[2:3], v18, v18, 1.0
	v_rcp_f32_e32 v50, v33
	v_div_scale_f32 v51, vcc, 1.0, v18, 1.0
	v_fma_f32 v52, -v33, v50, 1.0
	v_fmac_f32_e32 v50, v52, v50
	v_mul_f32_e32 v52, v51, v50
	v_fma_f32 v53, -v33, v52, v51
	v_fmac_f32_e32 v52, v53, v50
	v_fma_f32 v33, -v33, v52, v51
	v_div_fmas_f32 v33, v33, v50, v52
	v_div_fixup_f32 v33, v33, v18, 1.0
	v_mul_f32_e32 v42, v42, v33
	v_mul_f32_e32 v34, v34, v33
	v_mul_f32_e32 v43, v43, v33
	v_mul_f32_e32 v35, v35, v33
	v_bfe_u32 v50, v42, 16, 1
	v_bfe_u32 v52, v34, 16, 1
	v_bfe_u32 v51, v43, 16, 1
	v_bfe_u32 v53, v35, 16, 1
	v_add3_u32 v42, v42, v50, s18
	v_add3_u32 v34, v34, v52, s18
	v_add3_u32 v43, v43, v51, s18
	v_add3_u32 v35, v35, v53, s18
	v_lshrrev_b32_e32 v42, 16, v42
	v_lshrrev_b32_e32 v50, 16, v34
	v_mul_f32_e32 v44, v44, v33
	v_and_or_b32 v34, v43, s16, v42
	v_and_or_b32 v35, v35, s16, v50
	global_store_dwordx2 v[24:25], v[34:35], off
	v_mul_f32_e32 v34, v45, v33
	v_bfe_u32 v35, v44, 16, 1
	v_add3_u32 v35, v44, v35, s18
	v_bfe_u32 v42, v34, 16, 1
	v_lshrrev_b32_e32 v35, 16, v35
	v_add3_u32 v34, v34, v42, s18
	v_and_or_b32 v34, v34, s16, v35
	v_mul_f32_e32 v35, v36, v33
	v_mul_f32_e32 v36, v37, v33
	v_bfe_u32 v37, v35, 16, 1
	v_add3_u32 v35, v35, v37, s18
	v_bfe_u32 v37, v36, 16, 1
	v_lshrrev_b32_e32 v35, 16, v35
	v_add3_u32 v36, v36, v37, s18
	v_and_or_b32 v35, v36, s16, v35
	global_store_dwordx2 v[24:25], v[34:35], off offset:512
	v_mul_f32_e32 v34, v46, v33
	v_mul_f32_e32 v35, v47, v33
	v_bfe_u32 v36, v34, 16, 1
	v_add3_u32 v34, v34, v36, s18
	v_bfe_u32 v36, v35, 16, 1
	v_lshrrev_b32_e32 v34, 16, v34
	v_add3_u32 v35, v35, v36, s18
	v_and_or_b32 v34, v35, s16, v34
	v_mul_f32_e32 v35, v38, v33
	v_mul_f32_e32 v36, v39, v33
	v_bfe_u32 v37, v35, 16, 1
	v_add3_u32 v35, v35, v37, s18
	v_bfe_u32 v37, v36, 16, 1
	v_lshrrev_b32_e32 v35, 16, v35
	v_add3_u32 v36, v36, v37, s18
	v_and_or_b32 v35, v36, s16, v35
	global_store_dwordx2 v[24:25], v[34:35], off offset:1024
	v_mul_f32_e32 v34, v48, v33
	v_mul_f32_e32 v35, v49, v33
	v_bfe_u32 v36, v34, 16, 1
	v_add3_u32 v34, v34, v36, s18
	v_bfe_u32 v36, v35, 16, 1
	v_lshrrev_b32_e32 v34, 16, v34
	v_add3_u32 v35, v35, v36, s18
	v_and_or_b32 v34, v35, s16, v34
	v_mul_f32_e32 v35, v40, v33
	v_mul_f32_e32 v33, v41, v33
	v_bfe_u32 v36, v35, 16, 1
	v_add3_u32 v35, v35, v36, s18
	v_bfe_u32 v36, v33, 16, 1
	v_lshrrev_b32_e32 v35, 16, v35
	v_add3_u32 v33, v33, v36, s18
	v_and_or_b32 v35, v33, s16, v35
	global_store_dwordx2 v[24:25], v[34:35], off offset:1536
	s_and_saveexec_b64 s[2:3], s[0:1]
	s_cbranch_execz .LBB0_1126
	global_store_dword v19, v18, s[10:11]
	s_branch .LBB0_1126

.LBB0_1264:
	s_cmp_lt_i32 s88, 13
	s_cselect_b64 s[0:1], -1, 0
	s_and_b64 s[6:7], s[0:1], s[2:3]
	s_andn2_b64 vcc, exec, s[6:7]
	s_cbranch_vccnz .LBB0_1274
	s_lshl_b32 s12, s66, 3
	s_lshl_b32 s0, s66, 7
	s_and_b32 s0, s0, 0xfffff000
	s_and_b32 s1, s12, 0xf8
	s_add_i32 s2, s0, 0x1000
	s_or_b32 s3, s0, s1
	s_cmpk_eq_i32 s68, 0x100
	s_cselect_b64 s[8:9], -1, 0
	s_and_b64 s[0:1], s[8:9], exec
	s_cselect_b32 s13, s2, 0x8000
	s_cselect_b32 s2, s3, s12
	s_add_i32 s14, s2, s96
	s_cmp_ge_i32 s14, s13
	v_mov_b32_e32 v19, 0
	s_cbranch_scc1 .LBB0_1270
	v_lshlrev_b32_e32 v1, 4, v177
	global_load_dwordx4 v[2:5], v1, s[26:27]
	global_load_dwordx4 v[6:9], v1, s[26:27] offset:1024
	global_load_dwordx4 v[10:13], v1, s[26:27] offset:2048
	global_load_dwordx4 v[14:17], v1, s[26:27] offset:3072
	v_mbcnt_lo_u32_b32 v1, -1, 0
	v_mbcnt_hi_u32_b32 v18, -1, v1
	v_and_b32_e32 v1, 64, v18
	v_add_u32_e32 v20, 64, v1
	v_xor_b32_e32 v1, 1, v18
	v_cmp_lt_i32_e32 vcc, v1, v20
	v_xor_b32_e32 v21, 2, v18
	v_readlane_b32 s4, v252, 2
	v_cndmask_b32_e32 v1, v18, v1, vcc
	v_cmp_lt_i32_e32 vcc, v21, v20
	s_lshl_b32 s3, s68, 3
	v_readlane_b32 s5, v252, 3
	v_cndmask_b32_e32 v21, v18, v21, vcc
	v_lshlrev_b32_e32 v26, 2, v21
	v_xor_b32_e32 v21, 4, v18
	v_cmp_lt_i32_e32 vcc, v21, v20
	s_and_b64 s[0:1], s[8:9], exec
	s_cselect_b32 s15, 0x100, s3
	v_cndmask_b32_e32 v21, v18, v21, vcc
	v_lshlrev_b32_e32 v27, 2, v21
	v_xor_b32_e32 v21, 8, v18
	v_cmp_lt_i32_e32 vcc, v21, v20
	s_lshl_b32 s3, s66, 8
	s_and_b32 s3, s3, 0xffffe000
	v_cndmask_b32_e32 v21, v18, v21, vcc
	v_lshlrev_b32_e32 v28, 2, v21
	v_xor_b32_e32 v21, 16, v18
	v_cmp_lt_i32_e32 vcc, v21, v20
	s_add_i32 s3, s96, s3
	v_lshlrev_b32_e32 v1, 2, v1
	v_cndmask_b32_e32 v21, v18, v21, vcc
	v_lshlrev_b32_e32 v29, 2, v21
	v_xor_b32_e32 v21, 32, v18
	v_cmp_lt_i32_e32 vcc, v21, v20
	v_cmp_eq_u32_e64 s[0:1], 0, v177
	s_mov_b32 s17, 0xffff0000
	v_cndmask_b32_e32 v18, v18, v21, vcc
	v_lshlrev_b32_e32 v30, 2, v18
	v_lshlrev_b32_e32 v18, 3, v177
	v_lshl_add_u64 v[20:21], s[4:5], 0, v[18:19]
	v_readlane_b32 s4, v253, 52
	v_readlane_b32 s5, v253, 53
	v_mov_b32_e32 v31, 0x358637bd
	s_mov_b32 s18, 0xf800000
	s_waitcnt vmcnt(0)
	v_lshl_add_u64 v[22:23], s[4:5], 0, v[18:19]
	s_and_b32 s4, s66, 31
	s_lshl_b32 s4, s4, 4
	s_add_i32 s3, s3, s4
	s_sub_i32 s2, s3, s2
	s_add_i32 s16, s2, 0xf00
	v_mov_b32_e32 v32, 0x260
	s_movk_i32 s19, 0x7fff
	s_and_b64 s[2:3], s[8:9], exec
	s_cselect_b32 s2, s16, s14
	s_ashr_i32 s3, s2, 31
	s_lshl_b64 s[4:5], s[2:3], 11
	v_lshl_add_u64 v[98:99], v[20:21], 0, s[4:5]
	v_lshl_add_u64 v[100:101], v[22:23], 0, s[4:5]
	s_lshl_b64 s[2:3], s[2:3], 2
	s_add_u32 s2, s75, s2
	s_addc_u32 s3, s69, s3
	global_load_dwordx2 v[80:81], v[98:99], off
	global_load_dwordx2 v[82:83], v[98:99], off offset:512
	global_load_dwordx2 v[84:85], v[98:99], off offset:1024
	global_load_dwordx2 v[86:87], v[98:99], off offset:1536
	global_load_dwordx2 v[88:89], v[100:101], off
	global_load_dwordx2 v[90:91], v[100:101], off offset:512
	global_load_dwordx2 v[92:93], v[100:101], off offset:1024
	global_load_dwordx2 v[94:95], v[100:101], off offset:1536
	global_load_dword v96, v19, s[2:3]
	s_waitcnt vmcnt(0)
	s_branch .Lrp3_body

.Lrp3_body:
	v_mov_b32_e32 v34, v80
	v_mov_b32_e32 v35, v81
	v_mov_b32_e32 v36, v82
	v_mov_b32_e32 v37, v83
	v_mov_b32_e32 v38, v84
	v_mov_b32_e32 v39, v85
	v_mov_b32_e32 v40, v86
	v_mov_b32_e32 v41, v87
	v_mov_b32_e32 v42, v88
	v_mov_b32_e32 v43, v89
	v_mov_b32_e32 v44, v90
	v_mov_b32_e32 v45, v91
	v_mov_b32_e32 v46, v92
	v_mov_b32_e32 v47, v93
	v_mov_b32_e32 v48, v94
	v_mov_b32_e32 v49, v95
	v_mov_b32_e32 v18, v96
	s_and_b64 s[2:3], s[8:9], exec
	s_cselect_b32 s2, s16, s14
	s_ashr_i32 s3, s2, 31
	s_lshl_b64 s[4:5], s[2:3], 11
	s_lshl_b64 s[2:3], s[2:3], 2
	s_add_u32 s10, s75, s2
	v_lshl_add_u64 v[24:25], v[22:23], 0, s[4:5]
	s_addc_u32 s11, s69, s3
	s_add_i32 s2, s14, s15
	s_cmp_lt_i32 s2, s13
	s_cbranch_scc0 .Lrp3_skip
	s_sub_i32 s3, s16, s15
	s_and_b64 s[4:5], s[8:9], exec
	s_cselect_b32 s2, s3, s2
	s_ashr_i32 s3, s2, 31
	s_lshl_b64 s[4:5], s[2:3], 11
	v_lshl_add_u64 v[98:99], v[20:21], 0, s[4:5]
	v_lshl_add_u64 v[100:101], v[22:23], 0, s[4:5]
	s_lshl_b64 s[2:3], s[2:3], 2
	s_add_u32 s2, s75, s2
	s_addc_u32 s3, s69, s3
	global_load_dwordx2 v[80:81], v[98:99], off
	global_load_dwordx2 v[82:83], v[98:99], off offset:512
	global_load_dwordx2 v[84:85], v[98:99], off offset:1024
	global_load_dwordx2 v[86:87], v[98:99], off offset:1536
	global_load_dwordx2 v[88:89], v[100:101], off
	global_load_dwordx2 v[90:91], v[100:101], off offset:512
	global_load_dwordx2 v[92:93], v[100:101], off offset:1024
	global_load_dwordx2 v[94:95], v[100:101], off offset:1536
	global_load_dword v96, v19, s[2:3]
.Lrp3_skip:
	v_and_b32_e32 v51, 0xffff0000, v34
	v_alignbit_b32 v33, v35, v34, 16
	v_and_b32_e32 v35, 0xffff0000, v35
	v_lshlrev_b32_e32 v52, 16, v36
	v_and_b32_e32 v53, 0xffff0000, v36
	v_alignbit_b32 v36, v37, v36, 16
	v_and_b32_e32 v37, 0xffff0000, v37
	v_lshlrev_b32_e32 v50, 16, v34
	v_lshlrev_b32_e32 v54, 16, v38
	v_and_b32_e32 v55, 0xffff0000, v38
	v_alignbit_b32 v38, v39, v38, 16
	v_and_b32_e32 v39, 0xffff0000, v39
	v_and_b32_e32 v34, 0xffff0000, v33
	v_and_b32_e32 v36, 0xffff0000, v36
	v_mul_f32_e32 v33, v51, v51
	v_mul_f32_e32 v58, v35, v35
	v_mul_f32_e32 v59, v53, v53
	v_mul_f32_e32 v60, v37, v37
	v_lshlrev_b32_e32 v56, 16, v40
	v_and_b32_e32 v57, 0xffff0000, v40
	v_alignbit_b32 v40, v41, v40, 16
	v_and_b32_e32 v41, 0xffff0000, v41
	v_and_b32_e32 v38, 0xffff0000, v38
	v_mul_f32_e32 v61, v55, v55
	v_mul_f32_e32 v62, v39, v39
	v_fmac_f32_e32 v33, v50, v50
	v_fmac_f32_e32 v58, v34, v34
	v_fmac_f32_e32 v59, v52, v52
	v_fmac_f32_e32 v60, v36, v36
	v_and_b32_e32 v40, 0xffff0000, v40
	v_mul_f32_e32 v63, v57, v57
	v_mul_f32_e32 v64, v41, v41
	v_fmac_f32_e32 v61, v54, v54
	v_fmac_f32_e32 v62, v38, v38
	v_add_f32_e32 v33, v33, v58
	v_add_f32_e32 v58, v59, v60
	v_fmac_f32_e32 v63, v56, v56
	v_fmac_f32_e32 v64, v40, v40
	v_add_f32_e32 v59, v61, v62
	v_add_f32_e32 v33, v33, v58
	v_add_f32_e32 v60, v63, v64
	v_add_f32_e32 v33, v33, v59
	v_add_f32_e32 v33, v33, v60
	ds_bpermute_b32 v60, v1, v33
	v_lshlrev_b32_e32 v58, 16, v42
	v_and_b32_e32 v59, 0xffff0000, v42
	v_alignbit_b32 v42, v43, v42, 16
	v_and_b32_e32 v61, 0xffff0000, v44
	s_waitcnt lgkmcnt(0)
	v_add_f32_e32 v33, v33, v60
	ds_bpermute_b32 v62, v26, v33
	v_lshlrev_b32_e32 v60, 16, v44
	v_alignbit_b32 v44, v45, v44, 16
	v_pk_mul_f32 v[50:51], v[2:3], v[50:51]
	v_pk_mul_f32 v[52:53], v[6:7], v[52:53]
	s_waitcnt lgkmcnt(0)
	v_add_f32_e32 v33, v33, v62
	ds_bpermute_b32 v64, v27, v33
	v_pk_mul_f32 v[34:35], v[4:5], v[34:35]
	v_pk_mul_f32 v[36:37], v[8:9], v[36:37]
	v_and_b32_e32 v43, 0xffff0000, v43
	v_and_b32_e32 v45, 0xffff0000, v45
	s_waitcnt lgkmcnt(0)
	v_add_f32_e32 v33, v33, v64
	ds_bpermute_b32 v66, v28, v33
	v_and_b32_e32 v42, 0xffff0000, v42
	v_and_b32_e32 v44, 0xffff0000, v44
	v_lshlrev_b32_e32 v62, 16, v46
	v_and_b32_e32 v63, 0xffff0000, v46
	s_waitcnt lgkmcnt(0)
	v_add_f32_e32 v33, v33, v66
	ds_bpermute_b32 v66, v29, v33
	v_alignbit_b32 v46, v47, v46, 16
	v_pk_mul_f32 v[54:55], v[10:11], v[54:55]
	v_pk_mul_f32 v[38:39], v[12:13], v[38:39]
	v_and_b32_e32 v47, 0xffff0000, v47
	s_waitcnt lgkmcnt(0)
	v_add_f32_e32 v33, v33, v66
	ds_bpermute_b32 v66, v30, v33
	v_lshlrev_b32_e32 v64, 16, v48
	v_and_b32_e32 v65, 0xffff0000, v48
	v_alignbit_b32 v48, v49, v48, 16
	v_and_b32_e32 v46, 0xffff0000, v46
	s_waitcnt lgkmcnt(0)
	v_add_f32_e32 v33, v33, v66
	v_fmamk_f32 v33, v33, 0x3a800000, v31
	v_mul_f32_e32 v66, 0x4f800000, v33
	v_cmp_gt_f32_e32 vcc, s18, v33
	v_pk_mul_f32 v[56:57], v[14:15], v[56:57]
	v_pk_mul_f32 v[40:41], v[16:17], v[40:41]
	v_cndmask_b32_e32 v33, v33, v66, vcc
	v_sqrt_f32_e32 v66, v33
	v_and_b32_e32 v49, 0xffff0000, v49
	v_and_b32_e32 v48, 0xffff0000, v48
	v_add_u32_e32 v67, -1, v66
	v_add_u32_e32 v68, 1, v66
	v_fma_f32 v69, -v67, v66, v33
	v_fma_f32 v70, -v68, v66, v33
	v_cmp_ge_f32_e64 s[4:5], 0, v69
	s_nop 1
	v_cndmask_b32_e64 v66, v66, v67, s[4:5]
	v_cmp_lt_f32_e64 s[4:5], 0, v70
	s_nop 1
	v_cndmask_b32_e64 v66, v66, v68, s[4:5]
	v_mul_f32_e32 v67, 0x37800000, v66
	v_cndmask_b32_e32 v66, v66, v67, vcc
	v_cmp_class_f32_e32 vcc, v33, v32
	s_nop 1
	v_cndmask_b32_e32 v33, v66, v33, vcc
	v_div_scale_f32 v66, s[2:3], v33, v33, 1.0
	v_rcp_f32_e32 v67, v66
	v_div_scale_f32 v68, vcc, 1.0, v33, 1.0
	v_fma_f32 v69, -v66, v67, 1.0
	v_fmac_f32_e32 v67, v69, v67
	v_mul_f32_e32 v69, v68, v67
	v_fma_f32 v70, -v66, v69, v68
	v_fmac_f32_e32 v69, v70, v67
	v_fma_f32 v66, -v66, v69, v68
	v_div_fmas_f32 v66, v66, v67, v69
	v_div_fixup_f32 v66, v66, v33, 1.0
	v_pk_mul_f32 v[50:51], v[50:51], v[66:67] op_sel_hi:[1,0]
	v_pk_mul_f32 v[34:35], v[34:35], v[66:67] op_sel_hi:[1,0]
	v_pk_mul_f32 v[52:53], v[52:53], v[66:67] op_sel_hi:[1,0]
	v_pk_mul_f32 v[36:37], v[36:37], v[66:67] op_sel_hi:[1,0]
	v_pk_fma_f32 v[34:35], v[18:19], v[42:43], v[34:35] op_sel_hi:[0,1,1]
	v_pk_fma_f32 v[42:43], v[18:19], v[58:59], v[50:51] op_sel_hi:[0,1,1]
	v_pk_fma_f32 v[36:37], v[18:19], v[44:45], v[36:37] op_sel_hi:[0,1,1]
	v_pk_fma_f32 v[44:45], v[18:19], v[60:61], v[52:53] op_sel_hi:[0,1,1]
	v_pk_mul_f32 v[54:55], v[54:55], v[66:67] op_sel_hi:[1,0]
	v_pk_mul_f32 v[38:39], v[38:39], v[66:67] op_sel_hi:[1,0]
	v_mul_f32_e32 v33, v43, v43
	v_mul_f32_e32 v50, v35, v35
	v_mul_f32_e32 v51, v45, v45
	v_mul_f32_e32 v52, v37, v37
	v_pk_mul_f32 v[56:57], v[56:57], v[66:67] op_sel_hi:[1,0]
	v_pk_fma_f32 v[38:39], v[18:19], v[46:47], v[38:39] op_sel_hi:[0,1,1]
	v_pk_fma_f32 v[46:47], v[18:19], v[62:63], v[54:55] op_sel_hi:[0,1,1]
	v_fmac_f32_e32 v33, v42, v42
	v_fmac_f32_e32 v50, v34, v34
	v_fmac_f32_e32 v51, v44, v44
	v_fmac_f32_e32 v52, v36, v36
	v_pk_mul_f32 v[40:41], v[40:41], v[66:67] op_sel_hi:[1,0]
	v_mul_f32_e32 v53, v47, v47
	v_mul_f32_e32 v54, v39, v39
	v_add_f32_e32 v33, v33, v50
	v_add_f32_e32 v50, v51, v52
	v_pk_fma_f32 v[40:41], v[18:19], v[48:49], v[40:41] op_sel_hi:[0,1,1]
	v_pk_fma_f32 v[48:49], v[18:19], v[64:65], v[56:57] op_sel_hi:[0,1,1]
	v_fmac_f32_e32 v53, v46, v46
	v_fmac_f32_e32 v54, v38, v38
	v_add_f32_e32 v33, v33, v50
	v_mul_f32_e32 v18, v49, v49
	v_mul_f32_e32 v50, v41, v41
	v_add_f32_e32 v51, v53, v54
	v_fmac_f32_e32 v18, v48, v48
	v_fmac_f32_e32 v50, v40, v40
	v_add_f32_e32 v33, v51, v33
	v_add_f32_e32 v18, v18, v50
	v_add_f32_e32 v18, v18, v33
	ds_bpermute_b32 v33, v1, v18
	s_waitcnt lgkmcnt(0)
	v_add_f32_e32 v18, v18, v33
	ds_bpermute_b32 v33, v26, v18
	s_waitcnt lgkmcnt(0)
	v_add_f32_e32 v18, v18, v33
	ds_bpermute_b32 v33, v27, v18
	s_waitcnt lgkmcnt(0)
	v_add_f32_e32 v18, v18, v33
	ds_bpermute_b32 v33, v28, v18
	s_waitcnt lgkmcnt(0)
	v_add_f32_e32 v18, v18, v33
	ds_bpermute_b32 v33, v29, v18
	s_waitcnt lgkmcnt(0)
	v_add_f32_e32 v18, v18, v33
	ds_bpermute_b32 v33, v30, v18
	s_waitcnt lgkmcnt(0)
	v_add_f32_e32 v18, v18, v33
	v_fmamk_f32 v18, v18, 0x3a800000, v31
	v_mul_f32_e32 v33, 0x4f800000, v18
	v_cmp_gt_f32_e32 vcc, s18, v18
	s_nop 1
	v_cndmask_b32_e32 v18, v18, v33, vcc
	v_sqrt_f32_e32 v33, v18
	s_nop 0
	v_add_u32_e32 v50, -1, v33
	v_add_u32_e32 v51, 1, v33
	v_fma_f32 v52, -v50, v33, v18
	v_fma_f32 v53, -v51, v33, v18
	v_cmp_ge_f32_e64 s[4:5], 0, v52
	s_nop 1
	v_cndmask_b32_e64 v33, v33, v50, s[4:5]
	v_cmp_lt_f32_e64 s[4:5], 0, v53
	s_nop 1
	v_cndmask_b32_e64 v33, v33, v51, s[4:5]
	v_mul_f32_e32 v50, 0x37800000, v33
	v_cndmask_b32_e32 v33, v33, v50, vcc
	v_cmp_class_f32_e32 vcc, v18, v32
	s_nop 1
	v_cndmask_b32_e32 v18, v33, v18, vcc
	v_div_scale_f32 v33, s[2:3], v18, v18, 1.0
	v_rcp_f32_e32 v50, v33
	v_div_scale_f32 v51, vcc, 1.0, v18, 1.0
	v_fma_f32 v52, -v33, v50, 1.0
	v_fmac_f32_e32 v50, v52, v50
	v_mul_f32_e32 v52, v51, v50
	v_fma_f32 v53, -v33, v52, v51
	v_fmac_f32_e32 v52, v53, v50
	v_fma_f32 v33, -v33, v52, v51
	v_div_fmas_f32 v33, v33, v50, v52
	v_div_fixup_f32 v33, v33, v18, 1.0
	v_mul_f32_e32 v42, v42, v33
	v_mul_f32_e32 v34, v34, v33
	v_mul_f32_e32 v43, v43, v33
	v_mul_f32_e32 v35, v35, v33
	v_bfe_u32 v50, v42, 16, 1
	v_bfe_u32 v52, v34, 16, 1
	v_bfe_u32 v51, v43, 16, 1
	v_bfe_u32 v53, v35, 16, 1
	v_add3_u32 v42, v42, v50, s19
	v_add3_u32 v34, v34, v52, s19
	v_add3_u32 v43, v43, v51, s19
	v_add3_u32 v35, v35, v53, s19
	v_lshrrev_b32_e32 v42, 16, v42
	v_lshrrev_b32_e32 v50, 16, v34
	v_mul_f32_e32 v44, v44, v33
	v_and_or_b32 v34, v43, s17, v42
	v_and_or_b32 v35, v35, s17, v50
	global_store_dwordx2 v[24:25], v[34:35], off
	v_mul_f32_e32 v34, v45, v33
	v_bfe_u32 v35, v44, 16, 1
	v_add3_u32 v35, v44, v35, s19
	v_bfe_u32 v42, v34, 16, 1
	v_lshrrev_b32_e32 v35, 16, v35
	v_add3_u32 v34, v34, v42, s19
	v_and_or_b32 v34, v34, s17, v35
	v_mul_f32_e32 v35, v36, v33
	v_mul_f32_e32 v36, v37, v33
	v_bfe_u32 v37, v35, 16, 1
	v_add3_u32 v35, v35, v37, s19
	v_bfe_u32 v37, v36, 16, 1
	v_lshrrev_b32_e32 v35, 16, v35
	v_add3_u32 v36, v36, v37, s19
	v_and_or_b32 v35, v36, s17, v35
	global_store_dwordx2 v[24:25], v[34:35], off offset:512
	v_mul_f32_e32 v34, v46, v33
	v_mul_f32_e32 v35, v47, v33
	v_bfe_u32 v36, v34, 16, 1
	v_add3_u32 v34, v34, v36, s19
	v_bfe_u32 v36, v35, 16, 1
	v_lshrrev_b32_e32 v34, 16, v34
	v_add3_u32 v35, v35, v36, s19
	v_and_or_b32 v34, v35, s17, v34
	v_mul_f32_e32 v35, v38, v33
	v_mul_f32_e32 v36, v39, v33
	v_bfe_u32 v37, v35, 16, 1
	v_add3_u32 v35, v35, v37, s19
	v_bfe_u32 v37, v36, 16, 1
	v_lshrrev_b32_e32 v35, 16, v35
	v_add3_u32 v36, v36, v37, s19
	v_and_or_b32 v35, v36, s17, v35
	global_store_dwordx2 v[24:25], v[34:35], off offset:1024
	v_mul_f32_e32 v34, v48, v33
	v_mul_f32_e32 v35, v49, v33
	v_bfe_u32 v36, v34, 16, 1
	v_add3_u32 v34, v34, v36, s19
	v_bfe_u32 v36, v35, 16, 1
	v_lshrrev_b32_e32 v34, 16, v34
	v_add3_u32 v35, v35, v36, s19
	v_and_or_b32 v34, v35, s17, v34
	v_mul_f32_e32 v35, v40, v33
	v_mul_f32_e32 v33, v41, v33
	v_bfe_u32 v36, v35, 16, 1
	v_add3_u32 v35, v35, v36, s19
	v_bfe_u32 v36, v33, 16, 1
	v_lshrrev_b32_e32 v35, 16, v35
	v_add3_u32 v33, v33, v36, s19
	v_and_or_b32 v35, v33, s17, v35
	global_store_dwordx2 v[24:25], v[34:35], off offset:1536
	s_and_saveexec_b64 s[2:3], s[0:1]
	s_cbranch_execz .LBB0_1267
	global_store_dword v19, v18, s[10:11]
	s_branch .LBB0_1267

.LBB0_1478:
	s_lshl_b32 s2, s66, 3
	s_lshl_b32 s0, s66, 7
	s_and_b32 s0, s0, 0xfffff000
	s_and_b32 s1, s2, 0xf8
	s_add_i32 s3, s0, 0x1000
	s_or_b32 s8, s0, s1
	s_cmpk_eq_i32 s68, 0x100
	s_cselect_b64 s[6:7], -1, 0
	s_and_b64 s[0:1], s[6:7], exec
	s_cselect_b32 s2, s8, s2
	s_cselect_b32 s12, s3, 0x8000
	s_add_i32 s13, s2, s96
	s_cmp_lt_i32 s13, s12
	s_cbranch_scc0 .LBB0_1487
	v_mbcnt_lo_u32_b32 v32, -1, 0
	v_mbcnt_hi_u32_b32 v32, -1, v32
	v_and_b32_e32 v33, 64, v32
	v_add_u32_e32 v33, 64, v33
	v_xor_b32_e32 v34, 1, v32
	v_cmp_lt_i32_e32 vcc, v34, v33
	v_readlane_b32 s8, v252, 2
	s_lshl_b32 s3, s68, 3
	v_cndmask_b32_e32 v34, v32, v34, vcc
	v_lshlrev_b32_e32 v58, 2, v34
	v_xor_b32_e32 v34, 2, v32
	v_cmp_lt_i32_e32 vcc, v34, v33
	v_readlane_b32 s9, v252, 3
	s_and_b64 s[0:1], s[6:7], exec
	v_cndmask_b32_e32 v34, v32, v34, vcc
	v_lshlrev_b32_e32 v59, 2, v34
	v_xor_b32_e32 v34, 4, v32
	v_cmp_lt_i32_e32 vcc, v34, v33
	s_cselect_b32 s14, 0x100, s3
	s_lshl_b32 s3, s66, 8
	v_cndmask_b32_e32 v34, v32, v34, vcc
	v_lshlrev_b32_e32 v60, 2, v34
	v_xor_b32_e32 v34, 8, v32
	v_cmp_lt_i32_e32 vcc, v34, v33
	s_and_b32 s3, s3, 0xffffe000
	s_add_i32 s3, s96, s3
	v_cndmask_b32_e32 v34, v32, v34, vcc
	v_lshlrev_b32_e32 v61, 2, v34
	v_xor_b32_e32 v34, 16, v32
	v_cmp_lt_i32_e32 vcc, v34, v33
	v_cmp_eq_u32_e64 s[0:1], 0, v177
	s_mov_b32 s16, 0xffff0000
	v_cndmask_b32_e32 v34, v32, v34, vcc
	v_lshlrev_b32_e32 v62, 2, v34
	v_xor_b32_e32 v34, 32, v32
	v_cmp_lt_i32_e32 vcc, v34, v33
	v_mov_b32_e32 v33, 0
	v_mov_b32_e32 v39, v33
	v_cndmask_b32_e32 v32, v32, v34, vcc
	v_lshlrev_b32_e32 v63, 2, v32
	v_lshlrev_b32_e32 v32, 3, v177
	v_lshl_add_u64 v[34:35], s[8:9], 0, v[32:33]
	v_readlane_b32 s8, v253, 52
	v_readlane_b32 s9, v253, 53
	v_lshl_add_u64 v[38:39], s[76:77], 0, v[38:39]
	v_mov_b32_e32 v64, 0x358637bd
	v_lshl_add_u64 v[36:37], s[8:9], 0, v[32:33]
	s_and_b32 s8, s66, 31
	s_lshl_b32 s8, s8, 4
	s_add_i32 s3, s3, s8
	s_sub_i32 s2, s3, s2
	s_add_i32 s15, s2, 0xf00
	s_mov_b32 s17, 0xf800000
	v_mov_b32_e32 v65, 0x260
	s_movk_i32 s18, 0x7fff
	s_and_b64 s[2:3], s[6:7], exec
	s_cselect_b32 s2, s15, s13
	s_ashr_i32 s3, s2, 31
	s_lshl_b64 vcc, s[2:3], 11
	v_lshl_add_u64 v[118:119], v[34:35], 0, vcc
	v_lshl_add_u64 v[120:121], v[36:37], 0, vcc
	s_lshl_b64 s[2:3], s[2:3], 2
	s_add_u32 s2, s75, s2
	s_addc_u32 s3, s69, s3
	global_load_dwordx2 v[100:101], v[118:119], off
	global_load_dwordx2 v[102:103], v[118:119], off offset:512
	global_load_dwordx2 v[104:105], v[118:119], off offset:1024
	global_load_dwordx2 v[106:107], v[118:119], off offset:1536
	global_load_dwordx2 v[108:109], v[120:121], off
	global_load_dwordx2 v[110:111], v[120:121], off offset:512
	global_load_dwordx2 v[112:113], v[120:121], off offset:1024
	global_load_dwordx2 v[114:115], v[120:121], off offset:1536
	global_load_dword v116, v33, s[2:3]
	s_waitcnt vmcnt(0)
	s_branch .Lrp4_body

.LBB0_1482:
	s_waitcnt vmcnt(4)
.Lrp4_body:
	v_mov_b32_e32 v42, v100
	v_mov_b32_e32 v43, v101
	v_mov_b32_e32 v44, v102
	v_mov_b32_e32 v45, v103
	v_mov_b32_e32 v46, v104
	v_mov_b32_e32 v47, v105
	v_mov_b32_e32 v48, v106
	v_mov_b32_e32 v49, v107
	v_mov_b32_e32 v50, v108
	v_mov_b32_e32 v51, v109
	v_mov_b32_e32 v52, v110
	v_mov_b32_e32 v53, v111
	v_mov_b32_e32 v54, v112
	v_mov_b32_e32 v55, v113
	v_mov_b32_e32 v56, v114
	v_mov_b32_e32 v57, v115
	v_mov_b32_e32 v32, v116
	s_and_b64 s[2:3], s[6:7], exec
	s_cselect_b32 s10, s15, s13
	s_ashr_i32 s11, s10, 31
	s_lshl_b64 s[2:3], s[10:11], 11
	v_lshl_add_u64 v[40:41], v[36:37], 0, s[2:3]
	s_lshl_b64 s[2:3], s[10:11], 2
	s_add_u32 s8, s75, s2
	s_addc_u32 s9, s69, s3
	s_add_i32 s2, s13, s14
	s_cmp_lt_i32 s2, s12
	s_cbranch_scc0 .Lrp4_skip
	s_sub_i32 s3, s15, s14
	s_and_b64 vcc, s[6:7], exec
	s_cselect_b32 s2, s3, s2
	s_ashr_i32 s3, s2, 31
	s_lshl_b64 vcc, s[2:3], 11
	v_lshl_add_u64 v[118:119], v[34:35], 0, vcc
	v_lshl_add_u64 v[120:121], v[36:37], 0, vcc
	s_lshl_b64 s[2:3], s[2:3], 2
	s_add_u32 s2, s75, s2
	s_addc_u32 s3, s69, s3
	global_load_dwordx2 v[100:101], v[118:119], off
	global_load_dwordx2 v[102:103], v[118:119], off offset:512
	global_load_dwordx2 v[104:105], v[118:119], off offset:1024
	global_load_dwordx2 v[106:107], v[118:119], off offset:1536
	global_load_dwordx2 v[108:109], v[120:121], off
	global_load_dwordx2 v[110:111], v[120:121], off offset:512
	global_load_dwordx2 v[112:113], v[120:121], off offset:1024
	global_load_dwordx2 v[114:115], v[120:121], off offset:1536
	global_load_dword v116, v33, s[2:3]
.Lrp4_skip:
	v_lshlrev_b32_e32 v66, 16, v42
	v_and_b32_e32 v67, 0xffff0000, v42
	v_alignbit_b32 v42, v43, v42, 16
	v_and_b32_e32 v43, 0xffff0000, v43
	v_lshlrev_b32_e32 v68, 16, v44
	v_and_b32_e32 v69, 0xffff0000, v44
	v_alignbit_b32 v44, v45, v44, 16
	v_and_b32_e32 v45, 0xffff0000, v45
	v_lshlrev_b32_e32 v70, 16, v46
	v_and_b32_e32 v71, 0xffff0000, v46
	v_alignbit_b32 v46, v47, v46, 16
	v_and_b32_e32 v47, 0xffff0000, v47
	v_and_b32_e32 v42, 0xffff0000, v42
	v_and_b32_e32 v44, 0xffff0000, v44
	v_mul_f32_e32 v74, v67, v67
	v_mul_f32_e32 v75, v43, v43
	v_mul_f32_e32 v76, v69, v69
	v_mul_f32_e32 v77, v45, v45
	v_lshlrev_b32_e32 v72, 16, v48
	v_and_b32_e32 v73, 0xffff0000, v48
	v_alignbit_b32 v48, v49, v48, 16
	v_and_b32_e32 v49, 0xffff0000, v49
	v_and_b32_e32 v46, 0xffff0000, v46
	v_mul_f32_e32 v78, v71, v71
	v_mul_f32_e32 v79, v47, v47
	v_fmac_f32_e32 v74, v66, v66
	v_fmac_f32_e32 v75, v42, v42
	v_fmac_f32_e32 v76, v68, v68
	v_fmac_f32_e32 v77, v44, v44
	v_and_b32_e32 v48, 0xffff0000, v48
	v_mul_f32_e32 v80, v73, v73
	v_mul_f32_e32 v81, v49, v49
	v_fmac_f32_e32 v78, v70, v70
	v_fmac_f32_e32 v79, v46, v46
	v_add_f32_e32 v74, v74, v75
	v_add_f32_e32 v75, v76, v77
	v_fmac_f32_e32 v80, v72, v72
	v_fmac_f32_e32 v81, v48, v48
	v_add_f32_e32 v76, v78, v79
	v_add_f32_e32 v74, v74, v75
	v_add_f32_e32 v77, v80, v81
	v_add_f32_e32 v74, v74, v76
	v_add_f32_e32 v76, v74, v77
	ds_bpermute_b32 v77, v58, v76
	v_and_b32_e32 v81, 0xffff0000, v55
	v_and_b32_e32 v83, 0xffff0000, v56
	v_and_b32_e32 v85, 0xffff0000, v57
	v_lshlrev_b32_e32 v74, 16, v50
	s_waitcnt lgkmcnt(0)
	v_add_f32_e32 v78, v76, v77
	ds_bpermute_b32 v79, v59, v78
	v_and_b32_e32 v75, 0xffff0000, v50
	v_alignbit_b32 v50, v51, v50, 16
	v_lshlrev_b32_e32 v76, 16, v52
	v_and_b32_e32 v77, 0xffff0000, v52
	s_waitcnt lgkmcnt(0)
	v_add_f32_e32 v80, v78, v79
	ds_bpermute_b32 v82, v60, v80
	v_lshlrev_b32_e32 v78, 16, v54
	v_and_b32_e32 v79, 0xffff0000, v54
	v_alignbit_b32 v54, v55, v54, 16
	v_alignbit_b32 v52, v53, v52, 16
	s_waitcnt lgkmcnt(0)
	v_add_f32_e32 v55, v80, v82
	ds_bpermute_b32 v80, v61, v55
	v_lshlrev_b32_e32 v82, 16, v56
	v_alignbit_b32 v56, v57, v56, 16
	v_and_b32_e32 v84, 0xffff0000, v56
	v_pk_mul_f32 v[42:43], v[2:3], v[42:43]
	s_waitcnt lgkmcnt(0)
	v_add_f32_e32 v55, v55, v80
	ds_bpermute_b32 v57, v62, v55
	v_and_b32_e32 v80, 0xffff0000, v54
	v_pk_mul_f32 v[44:45], v[14:15], v[44:45]
	v_and_b32_e32 v51, 0xffff0000, v51
	v_and_b32_e32 v53, 0xffff0000, v53
	s_waitcnt lgkmcnt(0)
	v_add_f32_e32 v86, v55, v57
	ds_bpermute_b32 v87, v63, v86
	v_pk_mul_f32 v[54:55], v[0:1], v[66:67]
	v_pk_mul_f32 v[66:67], v[16:17], v[70:71]
	v_pk_mul_f32 v[56:57], v[12:13], v[68:69]
	v_pk_mul_f32 v[68:69], v[28:29], v[72:73]
	s_waitcnt lgkmcnt(0)
	v_add_f32_e32 v70, v86, v87
	v_fmamk_f32 v70, v70, 0x3a800000, v64
	v_mul_f32_e32 v71, 0x4f800000, v70
	v_cmp_gt_f32_e32 vcc, s17, v70
	v_and_b32_e32 v50, 0xffff0000, v50
	v_and_b32_e32 v52, 0xffff0000, v52
	v_cndmask_b32_e32 v70, v70, v71, vcc
	v_sqrt_f32_e32 v71, v70
	v_pk_mul_f32 v[46:47], v[18:19], v[46:47]
	v_pk_mul_f32 v[48:49], v[30:31], v[48:49]
	v_add_u32_e32 v72, -1, v71
	v_add_u32_e32 v73, 1, v71
	v_fma_f32 v86, -v72, v71, v70
	v_fma_f32 v87, -v73, v71, v70
	v_cmp_ge_f32_e64 s[2:3], 0, v86
	s_nop 1
	v_cndmask_b32_e64 v71, v71, v72, s[2:3]
	v_cmp_lt_f32_e64 s[2:3], 0, v87
	s_nop 1
	v_cndmask_b32_e64 v71, v71, v73, s[2:3]
	v_mul_f32_e32 v72, 0x37800000, v71
	v_cndmask_b32_e32 v71, v71, v72, vcc
	v_cmp_class_f32_e32 vcc, v70, v65
	s_nop 1
	v_cndmask_b32_e32 v70, v71, v70, vcc
	v_div_scale_f32 v71, s[2:3], v70, v70, 0.5
	v_rcp_f32_e32 v72, v71
	v_div_scale_f32 v73, vcc, 0.5, v70, 0.5
	v_fma_f32 v86, -v71, v72, 1.0
	v_fmac_f32_e32 v72, v86, v72
	v_mul_f32_e32 v86, v73, v72
	v_fma_f32 v87, -v71, v86, v73
	v_fmac_f32_e32 v86, v87, v72
	v_fma_f32 v71, -v71, v86, v73
	v_div_fmas_f32 v71, v71, v72, v86
	v_div_fixup_f32 v70, v71, v70, 0.5
	v_pk_mul_f32 v[72:73], v[54:55], v[70:71] op_sel_hi:[1,0]
	v_pk_mul_f32 v[42:43], v[42:43], v[70:71] op_sel_hi:[1,0]
	v_pk_mul_f32 v[86:87], v[56:57], v[70:71] op_sel_hi:[1,0]
	v_pk_mul_f32 v[44:45], v[44:45], v[70:71] op_sel_hi:[1,0]
	v_pk_mul_f32 v[66:67], v[66:67], v[70:71] op_sel_hi:[1,0]
	v_pk_mul_f32 v[46:47], v[46:47], v[70:71] op_sel_hi:[1,0]
	v_pk_fma_f32 v[54:55], v[32:33], v[50:51], v[42:43] op_sel_hi:[0,1,1]
	v_pk_fma_f32 v[56:57], v[32:33], v[74:75], v[72:73] op_sel_hi:[0,1,1]
	v_pk_fma_f32 v[50:51], v[32:33], v[52:53], v[44:45] op_sel_hi:[0,1,1]
	v_pk_fma_f32 v[52:53], v[32:33], v[76:77], v[86:87] op_sel_hi:[0,1,1]
	v_pk_fma_f32 v[42:43], v[32:33], v[80:81], v[46:47] op_sel_hi:[0,1,1]
	v_pk_fma_f32 v[46:47], v[32:33], v[78:79], v[66:67] op_sel_hi:[0,1,1]
	v_mul_f32_e32 v44, v57, v57
	v_mul_f32_e32 v45, v55, v55
	v_mul_f32_e32 v66, v53, v53
	v_mul_f32_e32 v67, v51, v51
	v_pk_mul_f32 v[68:69], v[68:69], v[70:71] op_sel_hi:[1,0]
	v_mul_f32_e32 v71, v47, v47
	v_mul_f32_e32 v72, v43, v43
	v_fmac_f32_e32 v44, v56, v56
	v_fmac_f32_e32 v45, v54, v54
	v_fmac_f32_e32 v66, v52, v52
	v_fmac_f32_e32 v67, v50, v50
	v_fmac_f32_e32 v71, v46, v46
	v_fmac_f32_e32 v72, v42, v42
	v_add_f32_e32 v44, v44, v45
	v_add_f32_e32 v45, v66, v67
	v_add_f32_e32 v66, v71, v72
	v_add_f32_e32 v44, v44, v45
	v_add_f32_e32 v66, v66, v44
	v_pk_mul_f32 v[44:45], v[48:49], v[70:71] op_sel_hi:[1,0]
	v_pk_fma_f32 v[48:49], v[32:33], v[82:83], v[68:69] op_sel_hi:[0,1,1]
	v_pk_fma_f32 v[44:45], v[32:33], v[84:85], v[44:45] op_sel_hi:[0,1,1]
	v_mul_f32_e32 v32, v49, v49
	v_mul_f32_e32 v67, v45, v45
	v_fmac_f32_e32 v32, v48, v48
	v_fmac_f32_e32 v67, v44, v44
	v_add_f32_e32 v32, v32, v67
	v_add_f32_e32 v32, v32, v66
	ds_bpermute_b32 v66, v58, v32
	s_waitcnt lgkmcnt(0)
	v_add_f32_e32 v32, v32, v66
	ds_bpermute_b32 v66, v59, v32
	s_waitcnt lgkmcnt(0)
	v_add_f32_e32 v32, v32, v66
	ds_bpermute_b32 v66, v60, v32
	s_waitcnt lgkmcnt(0)
	v_add_f32_e32 v32, v32, v66
	ds_bpermute_b32 v66, v61, v32
	s_waitcnt lgkmcnt(0)
	v_add_f32_e32 v32, v32, v66
	ds_bpermute_b32 v66, v62, v32
	s_waitcnt lgkmcnt(0)
	v_add_f32_e32 v32, v32, v66
	ds_bpermute_b32 v66, v63, v32
	s_waitcnt lgkmcnt(0)
	v_add_f32_e32 v32, v32, v66
	v_fmamk_f32 v32, v32, 0x3a800000, v64
	v_mul_f32_e32 v66, 0x4f800000, v32
	v_cmp_gt_f32_e32 vcc, s17, v32
	s_nop 1
	v_cndmask_b32_e32 v32, v32, v66, vcc
	v_sqrt_f32_e32 v66, v32
	s_nop 0
	v_add_u32_e32 v67, -1, v66
	v_add_u32_e32 v68, 1, v66
	v_fma_f32 v69, -v67, v66, v32
	v_fma_f32 v70, -v68, v66, v32
	v_cmp_ge_f32_e64 s[2:3], 0, v69
	s_nop 1
	v_cndmask_b32_e64 v66, v66, v67, s[2:3]
	v_cmp_lt_f32_e64 s[2:3], 0, v70
	s_nop 1
	v_cndmask_b32_e64 v66, v66, v68, s[2:3]
	v_mul_f32_e32 v67, 0x37800000, v66
	v_cndmask_b32_e32 v66, v66, v67, vcc
	v_cmp_class_f32_e32 vcc, v32, v65
	s_nop 1
	v_cndmask_b32_e32 v66, v66, v32, vcc
	v_div_scale_f32 v32, s[2:3], v66, v66, 1.0
	v_rcp_f32_e32 v67, v32
	v_div_scale_f32 v68, vcc, 1.0, v66, 1.0
	s_and_b64 s[2:3], exec, s[4:5]
	v_fma_f32 v69, -v32, v67, 1.0
	v_fmac_f32_e32 v67, v69, v67
	v_mul_f32_e32 v69, v68, v67
	v_fma_f32 v70, -v32, v69, v68
	v_fmac_f32_e32 v69, v70, v67
	v_fma_f32 v32, -v32, v69, v68
	v_div_fmas_f32 v32, v32, v67, v69
	v_div_fixup_f32 v32, v32, v66, 1.0
	s_mov_b64 vcc, s[2:3]
	s_cbranch_vccz .LBB0_1484
	s_lshl_b64 s[2:3], s[10:11], 10
	v_pk_mul_f32 v[70:71], v[10:11], v[54:55]
	v_pk_mul_f32 v[68:69], v[8:9], v[56:57]
	v_lshl_add_u64 v[72:73], s[2:3], 2, v[38:39]
	v_pk_mul_f32 v[68:69], v[68:69], v[32:33] op_sel_hi:[1,0]
	v_pk_mul_f32 v[70:71], v[70:71], v[32:33] op_sel_hi:[1,0]
	global_store_dwordx4 v[72:73], v[68:71], off
	s_nop 1
	v_pk_mul_f32 v[70:71], v[6:7], v[50:51]
	v_pk_mul_f32 v[68:69], v[4:5], v[52:53]
	v_pk_mul_f32 v[70:71], v[70:71], v[32:33] op_sel_hi:[1,0]
	v_pk_mul_f32 v[68:69], v[68:69], v[32:33] op_sel_hi:[1,0]
	global_store_dwordx4 v[72:73], v[68:71], off offset:1024
	s_nop 1
	v_pk_mul_f32 v[70:71], v[26:27], v[42:43]
	v_pk_mul_f32 v[68:69], v[24:25], v[46:47]
	v_pk_mul_f32 v[70:71], v[70:71], v[32:33] op_sel_hi:[1,0]
	v_pk_mul_f32 v[68:69], v[68:69], v[32:33] op_sel_hi:[1,0]
	global_store_dwordx4 v[72:73], v[68:71], off offset:2048
	s_nop 1
	v_pk_mul_f32 v[70:71], v[22:23], v[44:45]
	v_pk_mul_f32 v[68:69], v[20:21], v[48:49]
	v_pk_mul_f32 v[70:71], v[70:71], v[32:33] op_sel_hi:[1,0]
	v_pk_mul_f32 v[68:69], v[68:69], v[32:33] op_sel_hi:[1,0]
	global_store_dwordx4 v[72:73], v[68:71], off offset:3072
	s_cbranch_execnz .LBB0_1481
	s_branch .LBB0_1485
